# prompt attention loop: skip test first; the per-half global K/V prefetch issue (formerly before the block) now runs after the first two MFMAs and the LDS staging writes before MFMA 19, both inside the
# speedup vs baseline: 1.0113x; 1.0099x over previous
.LBB0_542:
	s_cmp_gt_u32 s52, s51
	s_cbranch_scc1 .Lh1_skip
	s_mul_i32 s61, s25, 0x2200
	s_and_b32 s42, s52, 2
	s_mulk_i32 s42, 0x3400
	v_add_u32_e32 v0, s42, v160
	v_add_u32_e32 v242, s61, v161
	v_add_u32_e32 v163, 0xe000, v242
	v_add_u32_e32 v242, 0xd000, v242
	ds_read_b128 v[82:85], v0 offset:13312
	ds_read_b128 v[98:101], v0 offset:19968
	ds_read_b128 v[164:167], v0 offset:13344
	ds_read_b128 v[168:171], v0 offset:20000
	ds_read2_b64 v[238:241], v242 offset0:0 offset1:2
	ds_read2_b64 v[234:237], v163 offset0:32 offset1:34
	ds_read_b128 v[172:175], v0 offset:13376
	ds_read_b128 v[176:179], v0 offset:20032
	ds_read_b128 v[180:183], v0 offset:13408
	ds_read_b128 v[184:187], v0 offset:20064
	ds_read_b128 v[188:191], v0 offset:13440
	ds_read_b128 v[192:195], v0 offset:20096
	ds_read_b128 v[196:199], v0 offset:13472
	ds_read_b128 v[220:223], v0 offset:20128
	v_exp_f32_e32 v50, v50
	v_exp_f32_e32 v51, v51
	v_exp_f32_e32 v52, v52
	v_exp_f32_e32 v53, v53
	v_exp_f32_e32 v54, v54
	v_exp_f32_e32 v55, v55
	v_exp_f32_e32 v56, v56
	v_exp_f32_e32 v57, v57
	s_waitcnt lgkmcnt(13)
	v_mfma_f32_32x32x16_bf16 v[82:97], v[82:85], v[122:125], 0
	v_cvt_pk_bf16_f32 v224, v50, v51
	v_cvt_pk_bf16_f32 v225, v52, v53
	v_cvt_pk_bf16_f32 v226, v54, v55
	v_cvt_pk_bf16_f32 v227, v56, v57
	v_exp_f32_e32 v58, v58
	v_add_f32_e32 v200, v50, v51
	s_waitcnt lgkmcnt(12)
	v_mfma_f32_32x32x16_bf16 v[98:113], v[98:101], v[122:125], 0
	v_exp_f32_e32 v59, v59
	v_exp_f32_e32 v60, v60
	v_add_f32_e32 v201, v52, v53
	v_exp_f32_e32 v61, v61
	s_add_i32 s60, s52, 3
	s_cmp_lt_u32 s60, s48
	s_cselect_b64 s[58:59], -1, 0
	s_cmp_ge_u32 s60, s48
	s_cbranch_scc1 .Lp1a_546
	s_waitcnt vmcnt(0)
	v_lshl_add_u64 v[2:3], s[54:55], 0, v[154:155]
	v_add_co_u32_e32 v2, vcc, 0xbe09000, v2
	s_nop 1
	v_addc_co_u32_e32 v3, vcc, 0, v3, vcc
	global_load_dwordx4 v[2:5], v[2:3], off
	s_and_saveexec_b64 s[42:43], s[40:41]
	s_cbranch_execz .Lp1a_545
	v_lshl_add_u64 v[10:11], s[54:55], 0, v[152:153]
	v_add_co_u32_e32 v10, vcc, 0xbe09000, v10
	s_nop 1
	v_addc_co_u32_e32 v11, vcc, 0, v11, vcc
	global_load_dwordx4 v[10:13], v[10:11], off

.Lp1a_end:
	s_waitcnt lgkmcnt(11)
	v_mfma_f32_32x32x16_bf16 v[82:97], v[164:167], v[126:129], v[82:97]
	v_exp_f32_e32 v62, v62
	v_add_f32_e32 v200, v200, v54
	v_exp_f32_e32 v63, v63
	v_add_f32_e32 v201, v201, v55
	v_exp_f32_e32 v64, v64
	s_waitcnt lgkmcnt(10)
	v_mfma_f32_32x32x16_bf16 v[98:113], v[168:171], v[126:129], v[98:113]
	ds_read2_b64 v[164:167], v242 offset0:4 offset1:6
	ds_read2_b64 v[168:171], v163 offset0:36 offset1:38
	v_add_f32_e32 v200, v200, v56
	v_exp_f32_e32 v65, v65
	v_add_f32_e32 v201, v201, v57
	v_cvt_pk_bf16_f32 v228, v58, v59
	v_cvt_pk_bf16_f32 v229, v60, v61
	s_waitcnt lgkmcnt(11)
	v_mfma_f32_32x32x16_bf16 v[18:33], v[238:241], v[224:227], v[18:33]
	v_cvt_pk_bf16_f32 v230, v62, v63
	v_cvt_pk_bf16_f32 v231, v64, v65
	v_exp_f32_e32 v66, v66
	v_add_f32_e32 v200, v200, v58
	v_exp_f32_e32 v67, v67
	v_add_f32_e32 v201, v201, v59
	s_waitcnt lgkmcnt(10)
	v_mfma_f32_32x32x16_bf16 v[34:49], v[234:237], v[224:227], v[34:49]
	v_exp_f32_e32 v68, v68
	v_add_f32_e32 v200, v200, v60
	v_exp_f32_e32 v69, v69
	v_add_f32_e32 v201, v201, v61
	v_exp_f32_e32 v70, v70
	s_waitcnt lgkmcnt(9)
	v_mfma_f32_32x32x16_bf16 v[82:97], v[172:175], v[134:137], v[82:97]
	v_add_f32_e32 v200, v200, v62
	v_exp_f32_e32 v71, v71
	v_add_f32_e32 v201, v201, v63
	v_exp_f32_e32 v72, v72
	v_add_f32_e32 v200, v200, v64
	s_waitcnt lgkmcnt(8)
	v_mfma_f32_32x32x16_bf16 v[98:113], v[176:179], v[134:137], v[98:113]
	ds_read2_b64 v[172:175], v242 offset0:8 offset1:10
	ds_read2_b64 v[176:179], v163 offset0:40 offset1:42
	v_exp_f32_e32 v73, v73
	v_add_f32_e32 v201, v201, v65
	v_cvt_pk_bf16_f32 v224, v66, v67
	v_cvt_pk_bf16_f32 v225, v68, v69
	v_cvt_pk_bf16_f32 v226, v70, v71
	s_waitcnt lgkmcnt(3)
	v_mfma_f32_32x32x16_bf16 v[18:33], v[164:167], v[228:231], v[18:33]
	v_cvt_pk_bf16_f32 v227, v72, v73
	v_exp_f32_e32 v74, v74
	v_add_f32_e32 v200, v200, v66
	v_exp_f32_e32 v75, v75
	v_add_f32_e32 v201, v201, v67
	s_waitcnt lgkmcnt(2)
	v_mfma_f32_32x32x16_bf16 v[34:49], v[168:171], v[228:231], v[34:49]
	v_exp_f32_e32 v76, v76
	v_add_f32_e32 v200, v200, v68
	v_exp_f32_e32 v77, v77
	v_add_f32_e32 v201, v201, v69
	v_exp_f32_e32 v78, v78
	s_waitcnt lgkmcnt(9)
	v_mfma_f32_32x32x16_bf16 v[82:97], v[180:183], v[138:141], v[82:97]
	v_add_f32_e32 v200, v200, v70
	v_exp_f32_e32 v79, v79
	v_add_f32_e32 v201, v201, v71
	v_exp_f32_e32 v80, v80
	v_add_f32_e32 v200, v200, v72
	s_waitcnt lgkmcnt(8)
	v_mfma_f32_32x32x16_bf16 v[98:113], v[184:187], v[138:141], v[98:113]
	ds_read2_b64 v[180:183], v242 offset0:12 offset1:14
	ds_read2_b64 v[184:187], v163 offset0:44 offset1:46
	v_exp_f32_e32 v81, v81
	v_add_f32_e32 v201, v201, v73
	v_cvt_pk_bf16_f32 v228, v74, v75
	v_cvt_pk_bf16_f32 v229, v76, v77
	v_cvt_pk_bf16_f32 v230, v78, v79
	s_waitcnt lgkmcnt(3)
	v_mfma_f32_32x32x16_bf16 v[18:33], v[172:175], v[224:227], v[18:33]
	v_cvt_pk_bf16_f32 v231, v80, v81
	v_add_f32_e32 v200, v200, v74
	v_add_f32_e32 v201, v201, v75
	v_add_f32_e32 v200, v200, v76
	v_add_f32_e32 v201, v201, v77
	v_add_f32_e32 v200, v200, v78
	v_add_f32_e32 v201, v201, v79
	v_add_f32_e32 v200, v200, v80
	s_waitcnt lgkmcnt(2)
	v_mfma_f32_32x32x16_bf16 v[34:49], v[176:179], v[224:227], v[34:49]
	v_add_f32_e32 v201, v201, v81
	v_add_f32_e32 v200, v200, v201
	v_add_f32_e32 v162, v162, v200
	s_waitcnt lgkmcnt(9)
	v_mfma_f32_32x32x16_bf16 v[82:97], v[188:191], v[142:145], v[82:97]
	s_waitcnt lgkmcnt(8)
	v_mfma_f32_32x32x16_bf16 v[98:113], v[192:195], v[142:145], v[98:113]
	s_waitcnt lgkmcnt(7)
	v_mfma_f32_32x32x16_bf16 v[82:97], v[196:199], v[146:149], v[82:97]
	s_waitcnt lgkmcnt(6)
	v_mfma_f32_32x32x16_bf16 v[98:113], v[220:223], v[146:149], v[98:113]
	s_waitcnt lgkmcnt(0)
	v_cndmask_b32_e64 v0, 0, 1, s[44:45]
	v_cmp_ne_u32_e64 s[42:43], 1, v0
	s_andn2_b64 vcc, exec, s[44:45]
	s_cbranch_vccnz .Lt1a_mid
	s_and_b32 s44, s53, 2
	s_mulk_i32 s44, 0x3400
	s_add_i32 s62, s44, 0
	v_add_u32_e32 v0, s62, v151
	s_waitcnt vmcnt(0)
	ds_write_b128 v0, v[118:121]
	s_and_saveexec_b64 s[44:45], s[40:41]
	v_add_u32_e32 v0, s62, v159
	ds_write_b128 v0, v[6:9]
	s_or_b64 exec, exec, s[44:45]

.Lt1a_end:
	v_mfma_f32_32x32x16_bf16 v[18:33], v[180:183], v[228:231], v[18:33]
	v_mfma_f32_32x32x16_bf16 v[34:49], v[184:187], v[228:231], v[34:49]
	s_branch .LBB0_556
.Lh1_skip:
	s_add_i32 s60, s52, 3
	s_cmp_lt_u32 s60, s48
	s_cselect_b64 s[58:59], -1, 0
	s_cmp_ge_u32 s60, s48
	s_cbranch_scc1 .LBB0_546
	s_waitcnt vmcnt(0)
	v_lshl_add_u64 v[2:3], s[54:55], 0, v[154:155]
	v_add_co_u32_e32 v2, vcc, 0xbe09000, v2
	s_nop 1
	v_addc_co_u32_e32 v3, vcc, 0, v3, vcc
	global_load_dwordx4 v[2:5], v[2:3], off
	s_and_saveexec_b64 s[42:43], s[40:41]
	s_cbranch_execz .LBB0_545
	v_lshl_add_u64 v[10:11], s[54:55], 0, v[152:153]
	v_add_co_u32_e32 v10, vcc, 0xbe09000, v10
	s_nop 1
	v_addc_co_u32_e32 v11, vcc, 0, v11, vcc
	global_load_dwordx4 v[10:13], v[10:11], off

.LBB0_548:
	s_mul_i32 s61, s25, 0x2200
	s_branch .LBB0_550

.LBB0_556:
	s_add_i32 s61, s25, 1
	s_cmp_lg_u32 s25, 2
	s_cselect_b32 s25, s61, 0
	s_andn2_b64 vcc, exec, s[44:45]
	s_waitcnt lgkmcnt(0)
	s_barrier
	s_cbranch_vccnz .LBB0_572
	s_cmp_ge_u32 s52, s51
	s_cbranch_scc1 .Lh2_skip
	s_andn2_b32 s62, 2, s52
	s_mulk_i32 s62, 0x3400
	v_add_u32_e32 v0, s62, v160
	s_mul_i32 s62, s25, 0x2200
	v_add_u32_e32 v242, s62, v161
	v_add_u32_e32 v163, 0xe000, v242
	v_add_u32_e32 v242, 0xd000, v242
	ds_read_b128 v[50:53], v0 offset:0
	ds_read_b128 v[66:69], v0 offset:6656
	ds_read_b128 v[164:167], v0 offset:32
	ds_read_b128 v[168:171], v0 offset:6688
	ds_read2_b64 v[238:241], v242 offset0:0 offset1:2
	ds_read2_b64 v[234:237], v163 offset0:32 offset1:34
	ds_read_b128 v[172:175], v0 offset:64
	ds_read_b128 v[176:179], v0 offset:6720
	ds_read_b128 v[180:183], v0 offset:96
	ds_read_b128 v[184:187], v0 offset:6752
	ds_read_b128 v[188:191], v0 offset:128
	ds_read_b128 v[192:195], v0 offset:6784
	ds_read_b128 v[196:199], v0 offset:160
	ds_read_b128 v[220:223], v0 offset:6816
	v_exp_f32_e32 v82, v82
	v_exp_f32_e32 v83, v83
	v_exp_f32_e32 v84, v84
	v_exp_f32_e32 v85, v85
	v_exp_f32_e32 v86, v86
	v_exp_f32_e32 v87, v87
	v_exp_f32_e32 v88, v88
	v_exp_f32_e32 v89, v89
	s_waitcnt lgkmcnt(13)
	v_mfma_f32_32x32x16_bf16 v[50:65], v[50:53], v[122:125], 0
	v_cvt_pk_bf16_f32 v224, v82, v83
	v_cvt_pk_bf16_f32 v225, v84, v85
	v_cvt_pk_bf16_f32 v226, v86, v87
	v_cvt_pk_bf16_f32 v227, v88, v89
	v_exp_f32_e32 v90, v90
	v_add_f32_e32 v200, v82, v83
	s_waitcnt lgkmcnt(12)
	v_mfma_f32_32x32x16_bf16 v[66:81], v[66:69], v[122:125], 0
	v_exp_f32_e32 v91, v91
	v_exp_f32_e32 v92, v92
	v_add_f32_e32 v201, v84, v85
	v_exp_f32_e32 v93, v93
	s_cmp_ge_u32 s52, s5
	s_cbranch_scc1 .Lp2a_561
	s_waitcnt vmcnt(0)
	v_lshl_add_u64 v[118:119], s[54:55], 0, v[154:155]
	v_add_co_u32_e32 v118, vcc, 0xbe0c000, v118
	s_nop 1
	v_addc_co_u32_e32 v119, vcc, 0, v119, vcc
	global_load_dwordx4 v[118:121], v[118:119], off
	s_and_saveexec_b64 s[44:45], s[40:41]
	s_cbranch_execz .Lp2a_560
	v_lshl_add_u64 v[6:7], s[54:55], 0, v[152:153]
	v_add_co_u32_e32 v6, vcc, 0xbe0c000, v6
	s_nop 1
	v_addc_co_u32_e32 v7, vcc, 0, v7, vcc
	global_load_dwordx4 v[6:9], v[6:7], off

.Lp2a_end:
	s_waitcnt lgkmcnt(11)
	v_mfma_f32_32x32x16_bf16 v[50:65], v[164:167], v[126:129], v[50:65]
	v_exp_f32_e32 v94, v94
	v_add_f32_e32 v200, v200, v86
	v_exp_f32_e32 v95, v95
	v_add_f32_e32 v201, v201, v87
	v_exp_f32_e32 v96, v96
	s_waitcnt lgkmcnt(10)
	v_mfma_f32_32x32x16_bf16 v[66:81], v[168:171], v[126:129], v[66:81]
	ds_read2_b64 v[164:167], v242 offset0:4 offset1:6
	ds_read2_b64 v[168:171], v163 offset0:36 offset1:38
	v_add_f32_e32 v200, v200, v88
	v_exp_f32_e32 v97, v97
	v_add_f32_e32 v201, v201, v89
	v_cvt_pk_bf16_f32 v228, v90, v91
	v_cvt_pk_bf16_f32 v229, v92, v93
	s_waitcnt lgkmcnt(11)
	v_mfma_f32_32x32x16_bf16 v[18:33], v[238:241], v[224:227], v[18:33]
	v_cvt_pk_bf16_f32 v230, v94, v95
	v_cvt_pk_bf16_f32 v231, v96, v97
	v_exp_f32_e32 v98, v98
	v_add_f32_e32 v200, v200, v90
	v_exp_f32_e32 v99, v99
	v_add_f32_e32 v201, v201, v91
	s_waitcnt lgkmcnt(10)
	v_mfma_f32_32x32x16_bf16 v[34:49], v[234:237], v[224:227], v[34:49]
	v_exp_f32_e32 v100, v100
	v_add_f32_e32 v200, v200, v92
	v_exp_f32_e32 v101, v101
	v_add_f32_e32 v201, v201, v93
	v_exp_f32_e32 v102, v102
	s_waitcnt lgkmcnt(9)
	v_mfma_f32_32x32x16_bf16 v[50:65], v[172:175], v[134:137], v[50:65]
	v_add_f32_e32 v200, v200, v94
	v_exp_f32_e32 v103, v103
	v_add_f32_e32 v201, v201, v95
	v_exp_f32_e32 v104, v104
	v_add_f32_e32 v200, v200, v96
	s_waitcnt lgkmcnt(8)
	v_mfma_f32_32x32x16_bf16 v[66:81], v[176:179], v[134:137], v[66:81]
	ds_read2_b64 v[172:175], v242 offset0:8 offset1:10
	ds_read2_b64 v[176:179], v163 offset0:40 offset1:42
	v_exp_f32_e32 v105, v105
	v_add_f32_e32 v201, v201, v97
	v_cvt_pk_bf16_f32 v224, v98, v99
	v_cvt_pk_bf16_f32 v225, v100, v101
	v_cvt_pk_bf16_f32 v226, v102, v103
	s_waitcnt lgkmcnt(3)
	v_mfma_f32_32x32x16_bf16 v[18:33], v[164:167], v[228:231], v[18:33]
	v_cvt_pk_bf16_f32 v227, v104, v105
	v_exp_f32_e32 v106, v106
	v_add_f32_e32 v200, v200, v98
	v_exp_f32_e32 v107, v107
	v_add_f32_e32 v201, v201, v99
	s_waitcnt lgkmcnt(2)
	v_mfma_f32_32x32x16_bf16 v[34:49], v[168:171], v[228:231], v[34:49]
	v_exp_f32_e32 v108, v108
	v_add_f32_e32 v200, v200, v100
	v_exp_f32_e32 v109, v109
	v_add_f32_e32 v201, v201, v101
	v_exp_f32_e32 v110, v110
	s_waitcnt lgkmcnt(9)
	v_mfma_f32_32x32x16_bf16 v[50:65], v[180:183], v[138:141], v[50:65]
	v_add_f32_e32 v200, v200, v102
	v_exp_f32_e32 v111, v111
	v_add_f32_e32 v201, v201, v103
	v_exp_f32_e32 v112, v112
	v_add_f32_e32 v200, v200, v104
	s_waitcnt lgkmcnt(8)
	v_mfma_f32_32x32x16_bf16 v[66:81], v[184:187], v[138:141], v[66:81]
	ds_read2_b64 v[180:183], v242 offset0:12 offset1:14
	ds_read2_b64 v[184:187], v163 offset0:44 offset1:46
	v_exp_f32_e32 v113, v113
	v_add_f32_e32 v201, v201, v105
	v_cvt_pk_bf16_f32 v228, v106, v107
	v_cvt_pk_bf16_f32 v229, v108, v109
	v_cvt_pk_bf16_f32 v230, v110, v111
	s_waitcnt lgkmcnt(3)
	v_mfma_f32_32x32x16_bf16 v[18:33], v[172:175], v[224:227], v[18:33]
	v_cvt_pk_bf16_f32 v231, v112, v113
	v_add_f32_e32 v200, v200, v106
	v_add_f32_e32 v201, v201, v107
	v_add_f32_e32 v200, v200, v108
	v_add_f32_e32 v201, v201, v109
	v_add_f32_e32 v200, v200, v110
	v_add_f32_e32 v201, v201, v111
	v_add_f32_e32 v200, v200, v112
	s_waitcnt lgkmcnt(2)
	v_mfma_f32_32x32x16_bf16 v[34:49], v[176:179], v[224:227], v[34:49]
	v_add_f32_e32 v201, v201, v113
	v_add_f32_e32 v200, v200, v201
	v_add_f32_e32 v162, v162, v200
	s_waitcnt lgkmcnt(9)
	v_mfma_f32_32x32x16_bf16 v[50:65], v[188:191], v[142:145], v[50:65]
	s_waitcnt lgkmcnt(8)
	v_mfma_f32_32x32x16_bf16 v[66:81], v[192:195], v[142:145], v[66:81]
	s_waitcnt lgkmcnt(7)
	v_mfma_f32_32x32x16_bf16 v[50:65], v[196:199], v[146:149], v[50:65]
	s_waitcnt lgkmcnt(6)
	v_mfma_f32_32x32x16_bf16 v[66:81], v[220:223], v[146:149], v[66:81]
	s_waitcnt lgkmcnt(0)
	s_mul_i32 s58, s25, 0x2200
	s_and_b64 vcc, exec, s[44:45]
	s_cbranch_vccnz .Lt2a_mid
	s_and_b32 s44, s60, 3
	s_mulk_i32 s44, 0x3400
	s_add_i32 s52, s44, 0
	v_add_u32_e32 v0, s52, v151
	s_waitcnt vmcnt(0)
	ds_write_b128 v0, v[2:5]
	s_and_saveexec_b64 s[44:45], s[40:41]
	v_add_u32_e32 v0, s52, v159
	ds_write_b128 v0, v[10:13]
	s_or_b64 exec, exec, s[44:45]

.Lh2_skip:
	s_cmp_ge_u32 s52, s5
	s_cbranch_scc1 .LBB0_561
	s_waitcnt vmcnt(0)
	v_lshl_add_u64 v[118:119], s[54:55], 0, v[154:155]
	v_add_co_u32_e32 v118, vcc, 0xbe0c000, v118
	s_nop 1
	v_addc_co_u32_e32 v119, vcc, 0, v119, vcc
	global_load_dwordx4 v[118:121], v[118:119], off
	s_and_saveexec_b64 s[44:45], s[40:41]
	s_cbranch_execz .LBB0_560
	v_lshl_add_u64 v[6:7], s[54:55], 0, v[152:153]
	v_add_co_u32_e32 v6, vcc, 0xbe0c000, v6
	s_nop 1
	v_addc_co_u32_e32 v7, vcc, 0, v7, vcc
	global_load_dwordx4 v[6:9], v[6:7], off

.LBB0_563:
	s_mul_i32 s58, s25, 0x2200
	s_branch .LBB0_565
